# dn_prep wave 0: gate-scalar wait and exp moved after the 24 conv-weight loads are issued (counted vmcnt), so the two global latencies overlap
# speedup vs baseline: 1.0035x; 1.0035x over previous
; DI void unpack8(u32x4 w, float* f) { f[0] = bflo(w.x); f[1] = bfhi(w.x); f[2] = bflo(w.y); f[3] = bfhi(w.y); f[4] = bflo(w.z); f[5] = bfhi(w.z); f[6] = bflo(w.w); f[7] = bfhi(w.w); }
; DI void dn_prep_item(const Params& p, int l, int item, int next_item, u32x4 (&pre)[12], unsigned char* lds, int tid) {
;     ...
;     const float* cw = p.in[12] + (size_t)l * 4 * 1536;
;     float da_raw = 0.f, db_raw = 0.f, dtb = 0.f, alog = 0.f;
;     if (tid < 64) { const size_t tok = (size_t)b * SEQL + n * 64 + tid; da_raw = DAB[tok * 16 + h]; db_raw = DAB[tok * 16 + 8 + h]; dtb = p.in[14][l * 8 + h]; alog = p.in[13][l * 8 + h]; }
;     {
;         const int i = tid >> 3, d0 = (tid & 7) * 8;
; #pragma unroll
;         for (int mat = 0; mat < 3; ++mat) { const int col = mat * 512 + h * 64 + d0; float a[8];
; #pragma unroll
;             for (int e = 0; e < 8; ++e) a[e] = 0.f;
; #pragma unroll
;             for (int j = 0; j < 4; ++j) { const int t = n * 64 + i - 3 + j;
;                 if (t >= 0) { float xv[8]; unpack8(pre[mat * 4 + j], xv);
;                     const f32x4 w0 = *(const f32x4*)(cw + j * 1536 + col), w1 = *(const f32x4*)(cw + j * 1536 + col + 4);
; #pragma unroll
;                     for (int e = 0; e < 4; ++e) { a[e] += w0[e] * xv[e]; a[4 + e] += w1[e] * xv[4 + e]; } } }
.LBB0_281:
	v_mov_b32_e32 v54, v166
	v_mov_b32_e32 v0, v165
	s_bfe_u32 s43, s42, 0x50003
	v_cmp_gt_i32_e64 s[6:7], 64, v54
	v_cmp_lt_i32_e32 vcc, 63, v54
	s_and_saveexec_b64 s[4:5], vcc
	s_xor_b64 s[4:5], exec, s[4:5]
	s_lshl_b32 s12, s43, 6
	s_or_saveexec_b64 s[10:11], s[4:5]
	s_load_dwordx2 s[8:9], s[0:1], 0x60
	s_and_b32 s4, s42, 7
	v_mov_b32_e32 v66, 0
	v_mov_b32_e32 v80, 1.0
	v_mov_b32_e32 v1, s12
	v_ashrrev_i32_e32 v55, 31, v54
	v_mov_b32_e32 v81, 0
	v_mov_b32_e32 v78, 0
	v_mov_b32_e32 v79, 0
	s_xor_b64 exec, exec, s[10:11]
	s_cbranch_execz .LBB0_285
	s_ashr_i32 s12, s42, 8
	s_ashr_i32 s13, s12, 31
	s_lshl_b64 s[12:13], s[12:13], 11
	s_lshl_b32 s5, s43, 6
	s_or_b32 s12, s12, s5
	v_lshl_add_u64 v[56:57], s[12:13], 0, v[54:55]
	v_lshlrev_b64 v[56:57], 6, v[56:57]
	v_lshl_add_u64 v[56:57], s[16:17], 0, v[56:57]
	s_lshl_b32 s66, s4, 2
	v_lshl_add_u64 v[56:57], v[56:57], 0, s[66:67]
	global_load_dword v79, v[56:57], off
	global_load_dword v78, v[56:57], off offset:32
	s_load_dwordx4 s[12:15], s[0:1], 0x68
	s_or_b32 s22, s4, s41
	s_ashr_i32 s23, s22, 31
	s_lshl_b64 s[22:23], s[22:23], 2
	s_waitcnt lgkmcnt(0)
	s_add_u32 s14, s14, s22
	s_addc_u32 s15, s15, s23
	s_add_u32 s12, s12, s22
	s_addc_u32 s13, s13, s23
	global_load_dword v81, v165, s[14:15]
	global_load_dword v244, v165, s[12:13]
	v_mov_b32_e32 v1, s5
.LBB0_285:
	s_or_b64 exec, exec, s[10:11]
	v_lshlrev_b32_e32 v56, 3, v54
	s_mul_i32 s5, s20, 0x6000
	v_ashrrev_i32_e32 v77, 3, v54
	v_and_b32_e32 v82, 56, v56
	s_waitcnt lgkmcnt(0)
	s_add_u32 s8, s8, s5
	s_mul_hi_i32 s5, s20, 0x6000
	v_add_u32_e32 v83, v1, v77
	v_lshlrev_b32_e32 v1, 2, v82
	s_addc_u32 s9, s9, s5
	v_lshl_or_b32 v164, s4, 8, v1
	v_lshl_add_u64 v[56:57], s[8:9], 0, v[164:165]
	s_mov_b64 s[22:23], 0x3000
	v_lshl_add_u64 v[190:191], v[56:57], 0, s[22:23]
	s_mov_b64 s[22:23], 0x1000
	v_lshl_add_u64 v[192:193], v[56:57], 0, s[22:23]
	s_mov_b64 s[22:23], 0x4000
	v_lshl_add_u64 v[194:195], v[56:57], 0, s[22:23]
	s_mov_b64 s[22:23], 0x2000
	v_lshl_add_u64 v[196:197], v[56:57], 0, s[22:23]
	s_mov_b64 s[22:23], 0x5000
	v_lshl_add_u64 v[198:199], v[56:57], 0, s[22:23]
	global_load_dwordx4 v[88:91], v[56:57], off offset:16
	global_load_dwordx4 v[92:95], v[56:57], off
	global_load_dwordx4 v[96:99], v[190:191], off
	global_load_dwordx4 v[100:103], v[190:191], off offset:16
	global_load_dwordx4 v[104:107], v[192:193], off offset:2048
	global_load_dwordx4 v[108:111], v[192:193], off offset:2064
	global_load_dwordx4 v[112:115], v[194:195], off offset:2048
	global_load_dwordx4 v[116:119], v[194:195], off offset:2064
	global_load_dwordx4 v[120:123], v[56:57], off offset:2064
	global_load_dwordx4 v[124:127], v[56:57], off offset:2048
	global_load_dwordx4 v[128:131], v[190:191], off offset:2048
	global_load_dwordx4 v[132:135], v[190:191], off offset:2064
	global_load_dwordx4 v[136:139], v[196:197], off
	global_load_dwordx4 v[140:143], v[196:197], off offset:16
	global_load_dwordx4 v[144:147], v[198:199], off
	global_load_dwordx4 v[148:151], v[198:199], off offset:16
	global_load_dwordx4 v[152:155], v[192:193], off
	global_load_dwordx4 v[156:159], v[192:193], off offset:16
	global_load_dwordx4 v[160:163], v[194:195], off
	global_load_dwordx4 v[170:173], v[194:195], off offset:16
	global_load_dwordx4 v[174:177], v[196:197], off offset:2048
	global_load_dwordx4 v[178:181], v[196:197], off offset:2064
	global_load_dwordx4 v[182:185], v[198:199], off offset:2048
	global_load_dwordx4 v[186:189], v[198:199], off offset:2064
	s_and_saveexec_b64 s[22:23], s[6:7]
	s_cbranch_execz .Lgate_done
	s_waitcnt vmcnt(24)
	v_mul_f32_e32 v212, 0x3fb8aa3b, v244
	v_fma_f32 v213, v244, s88, -v212
	v_rndne_f32_e32 v214, v212
	v_fmac_f32_e32 v213, 0x32a5705f, v244
	v_sub_f32_e32 v212, v212, v214
	v_add_f32_e32 v212, v212, v213
	v_exp_f32_e32 v212, v212
	v_cvt_i32_f32_e32 v213, v214
	v_cmp_ngt_f32_e32 vcc, s79, v244
	v_ldexp_f32 v212, v212, v213
	s_nop 0
	v_cndmask_b32_e32 v212, 0, v212, vcc
	v_cmp_nlt_f32_e32 vcc, s54, v244
	s_nop 1
	v_cndmask_b32_e32 v80, v210, v212, vcc
.Lgate_done:
	s_or_b64 exec, exec, s[22:23]
	v_cmp_lt_i32_e64 s[14:15], 2, v83
	v_mov_b32_e32 v67, 0
	v_mov_b32_e32 v58, 0
	v_mov_b32_e32 v59, 0
	v_mov_b32_e32 v62, 0
	v_mov_b32_e32 v63, 0
	v_mov_b32_e32 v60, 0
	v_mov_b32_e32 v61, 0
	v_mov_b32_e32 v64, 0
	v_mov_b32_e32 v65, 0
	s_and_saveexec_b64 s[8:9], s[14:15]
	s_cbranch_execz .LBB0_289
	s_waitcnt vmcnt(0)
	v_lshlrev_b32_e32 v58, 16, v46
	v_and_b32_e32 v59, 0xffff0000, v46
	v_lshlrev_b32_e32 v60, 16, v48
	v_and_b32_e32 v61, 0xffff0000, v48
	v_lshlrev_b32_e32 v46, 16, v47
	v_and_b32_e32 v47, 0xffff0000, v47
	s_waitcnt vmcnt(0)
	v_pk_fma_f32 v[60:61], v[88:89], v[60:61], 0 op_sel_hi:[1,1,0]
	s_waitcnt vmcnt(0)
	v_pk_fma_f32 v[62:63], v[94:95], v[46:47], 0 op_sel_hi:[1,1,0]
	v_lshlrev_b32_e32 v46, 16, v49
	v_and_b32_e32 v47, 0xffff0000, v49
	v_pk_fma_f32 v[66:67], v[90:91], v[46:47], 0 op_sel_hi:[1,1,0]
	v_pk_fma_f32 v[58:59], v[92:93], v[58:59], 0 op_sel_hi:[1,1,0]
	v_mov_b32_e32 v64, v66
	v_mov_b32_e32 v65, v67
	s_or_b64 exec, exec, s[8:9]
	v_cmp_lt_i32_e64 s[8:9], 1, v83
	s_and_saveexec_b64 s[10:11], s[8:9]
	s_cbranch_execnz .LBB0_290
